# P0 gW/bW reduction loop hand-pipelined: 4 groups of 12 loads in flight, saddr row bases, scalar v_fmac chain in the same k order
# baseline (speedup 1.0000x reference)
.LBB0_59:
	s_lshl_b32 s8, s13, 13
	v_readlane_b32 s44, v252, 8
	s_and_b32 s40, s8, 0xf00000
	s_lshl_b32 s8, s15, 2
	s_ashr_i32 s20, s31, 9
	v_readlane_b32 s45, v252, 9
	v_readlane_b32 s46, v252, 10
	v_readlane_b32 s47, v252, 11
	v_readlane_b32 s48, v252, 12
	v_readlane_b32 s49, v252, 13
	s_and_b32 s41, s8, 0x1f00
	s_lshl_b32 s8, s13, 2
	s_ashr_i32 s21, s20, 31
	v_readlane_b32 s50, v252, 14
	v_readlane_b32 s51, v252, 15
	s_mov_b64 s[44:45], s[48:49]
	s_and_b32 s33, s8, 0x1e00
	s_lshl_b64 s[38:39], s[20:21], 24
	s_lshl_b64 s[8:9], s[20:21], 12
	s_lshl_b64 s[20:21], s[20:21], 14
	s_mov_b64 s[46:47], s[50:51]
	s_add_u32 s34, s46, s20
	s_addc_u32 s35, s47, s21
	v_readlane_b32 s44, v252, 0
	v_readlane_b32 s45, v252, 1
	s_add_u32 s36, s44, s20
	s_addc_u32 s37, s45, s21
	s_or_b32 s20, s38, s40
	s_or_b32 s38, s20, s41
	v_lshl_add_u64 v[14:15], v[6:7], 0, s[38:39]
	s_mov_b64 s[20:21], 0
	v_mov_b32_e32 v12, 0
	v_mov_b32_e32 v13, v9
	v_readlane_b32 s46, v252, 2
	v_readlane_b32 s47, v252, 3
	v_readlane_b32 s48, v252, 4
	v_readlane_b32 s49, v252, 5
	v_readlane_b32 s50, v252, 6
	v_readlane_b32 s51, v252, 7
	v_readlane_b32 s100, v252, 32
	v_readlane_b32 s101, v252, 33
	s_add_u32 s34, s34, s33
	s_addc_u32 s35, s35, 0
	s_add_u32 s36, s36, s33
	s_addc_u32 s37, s37, 0
	s_add_u32 s100, s100, s38
	s_addc_u32 s101, s101, s39
	global_load_dwordx4 v[60:63], v9, s[34:35] offset:0
	global_load_dwordx4 v[64:67], v9, s[34:35] offset:16
	global_load_dwordx4 v[68:71], v9, s[36:37] offset:0
	global_load_dwordx4 v[72:75], v9, s[36:37] offset:16
	global_load_dword v76, v4, s[100:101]
	s_add_u32 s100, s100, 0x2000
	s_addc_u32 s101, s101, 0
	global_load_dword v77, v4, s[100:101]
	s_add_u32 s100, s100, 0x2000
	s_addc_u32 s101, s101, 0
	global_load_dword v78, v4, s[100:101]
	s_add_u32 s100, s100, 0x2000
	s_addc_u32 s101, s101, 0
	global_load_dword v79, v4, s[100:101]
	s_add_u32 s100, s100, 0x2000
	s_addc_u32 s101, s101, 0
	global_load_dword v80, v4, s[100:101]
	s_add_u32 s100, s100, 0x2000
	s_addc_u32 s101, s101, 0
	global_load_dword v81, v4, s[100:101]
	s_add_u32 s100, s100, 0x2000
	s_addc_u32 s101, s101, 0
	global_load_dword v82, v4, s[100:101]
	s_add_u32 s100, s100, 0x2000
	s_addc_u32 s101, s101, 0
	global_load_dword v83, v4, s[100:101]
	s_add_u32 s100, s100, 0x2000
	s_addc_u32 s101, s101, 0
	global_load_dwordx4 v[84:87], v9, s[34:35] offset:32
	global_load_dwordx4 v[88:91], v9, s[34:35] offset:48
	global_load_dwordx4 v[92:95], v9, s[36:37] offset:32
	global_load_dwordx4 v[96:99], v9, s[36:37] offset:48
	global_load_dword v100, v4, s[100:101]
	s_add_u32 s100, s100, 0x2000
	s_addc_u32 s101, s101, 0
	global_load_dword v101, v4, s[100:101]
	s_add_u32 s100, s100, 0x2000
	s_addc_u32 s101, s101, 0
	global_load_dword v102, v4, s[100:101]
	s_add_u32 s100, s100, 0x2000
	s_addc_u32 s101, s101, 0
	global_load_dword v103, v4, s[100:101]
	s_add_u32 s100, s100, 0x2000
	s_addc_u32 s101, s101, 0
	global_load_dword v104, v4, s[100:101]
	s_add_u32 s100, s100, 0x2000
	s_addc_u32 s101, s101, 0
	global_load_dword v105, v4, s[100:101]
	s_add_u32 s100, s100, 0x2000
	s_addc_u32 s101, s101, 0
	global_load_dword v106, v4, s[100:101]
	s_add_u32 s100, s100, 0x2000
	s_addc_u32 s101, s101, 0
	global_load_dword v107, v4, s[100:101]
	s_add_u32 s100, s100, 0x2000
	s_addc_u32 s101, s101, 0
	global_load_dwordx4 v[108:111], v9, s[34:35] offset:64
	global_load_dwordx4 v[112:115], v9, s[34:35] offset:80
	global_load_dwordx4 v[116:119], v9, s[36:37] offset:64
	global_load_dwordx4 v[120:123], v9, s[36:37] offset:80
	global_load_dword v124, v4, s[100:101]
	s_add_u32 s100, s100, 0x2000
	s_addc_u32 s101, s101, 0
	global_load_dword v125, v4, s[100:101]
	s_add_u32 s100, s100, 0x2000
	s_addc_u32 s101, s101, 0
	global_load_dword v126, v4, s[100:101]
	s_add_u32 s100, s100, 0x2000
	s_addc_u32 s101, s101, 0
	global_load_dword v127, v4, s[100:101]
	s_add_u32 s100, s100, 0x2000
	s_addc_u32 s101, s101, 0
	global_load_dword v128, v4, s[100:101]
	s_add_u32 s100, s100, 0x2000
	s_addc_u32 s101, s101, 0
	global_load_dword v129, v4, s[100:101]
	s_add_u32 s100, s100, 0x2000
	s_addc_u32 s101, s101, 0
	global_load_dword v130, v4, s[100:101]
	s_add_u32 s100, s100, 0x2000
	s_addc_u32 s101, s101, 0
	global_load_dword v131, v4, s[100:101]
	s_add_u32 s100, s100, 0x2000
	s_addc_u32 s101, s101, 0
	global_load_dwordx4 v[132:135], v9, s[34:35] offset:96
	global_load_dwordx4 v[136:139], v9, s[34:35] offset:112
	global_load_dwordx4 v[140:143], v9, s[36:37] offset:96
	global_load_dwordx4 v[144:147], v9, s[36:37] offset:112
	global_load_dword v148, v4, s[100:101]
	s_add_u32 s100, s100, 0x2000
	s_addc_u32 s101, s101, 0
	global_load_dword v149, v4, s[100:101]
	s_add_u32 s100, s100, 0x2000
	s_addc_u32 s101, s101, 0
	global_load_dword v150, v4, s[100:101]
	s_add_u32 s100, s100, 0x2000
	s_addc_u32 s101, s101, 0
	global_load_dword v151, v4, s[100:101]
	s_add_u32 s100, s100, 0x2000
	s_addc_u32 s101, s101, 0
	global_load_dword v152, v4, s[100:101]
	s_add_u32 s100, s100, 0x2000
	s_addc_u32 s101, s101, 0
	global_load_dword v153, v4, s[100:101]
	s_add_u32 s100, s100, 0x2000
	s_addc_u32 s101, s101, 0
	global_load_dword v154, v4, s[100:101]
	s_add_u32 s100, s100, 0x2000
	s_addc_u32 s101, s101, 0
	global_load_dword v155, v4, s[100:101]
	s_add_u32 s100, s100, 0x2000
	s_addc_u32 s101, s101, 0
	s_waitcnt vmcnt(36)
	v_fmac_f32_e32 v12, v76, v60
	v_fmac_f32_e32 v13, v76, v68
	v_fmac_f32_e32 v12, v77, v61
	v_fmac_f32_e32 v13, v77, v69
	v_fmac_f32_e32 v12, v78, v62
	v_fmac_f32_e32 v13, v78, v70
	v_fmac_f32_e32 v12, v79, v63
	v_fmac_f32_e32 v13, v79, v71
	v_fmac_f32_e32 v12, v80, v64
	v_fmac_f32_e32 v13, v80, v72
	v_fmac_f32_e32 v12, v81, v65
	v_fmac_f32_e32 v13, v81, v73
	v_fmac_f32_e32 v12, v82, v66
	v_fmac_f32_e32 v13, v82, v74
	v_fmac_f32_e32 v12, v83, v67
	v_fmac_f32_e32 v13, v83, v75
	global_load_dwordx4 v[60:63], v9, s[34:35] offset:128
	global_load_dwordx4 v[64:67], v9, s[34:35] offset:144
	global_load_dwordx4 v[68:71], v9, s[36:37] offset:128
	global_load_dwordx4 v[72:75], v9, s[36:37] offset:144
	global_load_dword v76, v4, s[100:101]
	s_add_u32 s100, s100, 0x2000
	s_addc_u32 s101, s101, 0
	global_load_dword v77, v4, s[100:101]
	s_add_u32 s100, s100, 0x2000
	s_addc_u32 s101, s101, 0
	global_load_dword v78, v4, s[100:101]
	s_add_u32 s100, s100, 0x2000
	s_addc_u32 s101, s101, 0
	global_load_dword v79, v4, s[100:101]
	s_add_u32 s100, s100, 0x2000
	s_addc_u32 s101, s101, 0
	global_load_dword v80, v4, s[100:101]
	s_add_u32 s100, s100, 0x2000
	s_addc_u32 s101, s101, 0
	global_load_dword v81, v4, s[100:101]
	s_add_u32 s100, s100, 0x2000
	s_addc_u32 s101, s101, 0
	global_load_dword v82, v4, s[100:101]
	s_add_u32 s100, s100, 0x2000
	s_addc_u32 s101, s101, 0
	global_load_dword v83, v4, s[100:101]
	s_add_u32 s100, s100, 0x2000
	s_addc_u32 s101, s101, 0
	s_waitcnt vmcnt(36)
	v_fmac_f32_e32 v12, v100, v84
	v_fmac_f32_e32 v13, v100, v92
	v_fmac_f32_e32 v12, v101, v85
	v_fmac_f32_e32 v13, v101, v93
	v_fmac_f32_e32 v12, v102, v86
	v_fmac_f32_e32 v13, v102, v94
	v_fmac_f32_e32 v12, v103, v87
	v_fmac_f32_e32 v13, v103, v95
	v_fmac_f32_e32 v12, v104, v88
	v_fmac_f32_e32 v13, v104, v96
	v_fmac_f32_e32 v12, v105, v89
	v_fmac_f32_e32 v13, v105, v97
	v_fmac_f32_e32 v12, v106, v90
	v_fmac_f32_e32 v13, v106, v98
	v_fmac_f32_e32 v12, v107, v91
	v_fmac_f32_e32 v13, v107, v99
	global_load_dwordx4 v[84:87], v9, s[34:35] offset:160
	global_load_dwordx4 v[88:91], v9, s[34:35] offset:176
	global_load_dwordx4 v[92:95], v9, s[36:37] offset:160
	global_load_dwordx4 v[96:99], v9, s[36:37] offset:176
	global_load_dword v100, v4, s[100:101]
	s_add_u32 s100, s100, 0x2000
	s_addc_u32 s101, s101, 0
	global_load_dword v101, v4, s[100:101]
	s_add_u32 s100, s100, 0x2000
	s_addc_u32 s101, s101, 0
	global_load_dword v102, v4, s[100:101]
	s_add_u32 s100, s100, 0x2000
	s_addc_u32 s101, s101, 0
	global_load_dword v103, v4, s[100:101]
	s_add_u32 s100, s100, 0x2000
	s_addc_u32 s101, s101, 0
	global_load_dword v104, v4, s[100:101]
	s_add_u32 s100, s100, 0x2000
	s_addc_u32 s101, s101, 0
	global_load_dword v105, v4, s[100:101]
	s_add_u32 s100, s100, 0x2000
	s_addc_u32 s101, s101, 0
	global_load_dword v106, v4, s[100:101]
	s_add_u32 s100, s100, 0x2000
	s_addc_u32 s101, s101, 0
	global_load_dword v107, v4, s[100:101]
	s_add_u32 s100, s100, 0x2000
	s_addc_u32 s101, s101, 0
	s_waitcnt vmcnt(36)
	v_fmac_f32_e32 v12, v124, v108
	v_fmac_f32_e32 v13, v124, v116
	v_fmac_f32_e32 v12, v125, v109
	v_fmac_f32_e32 v13, v125, v117
	v_fmac_f32_e32 v12, v126, v110
	v_fmac_f32_e32 v13, v126, v118
	v_fmac_f32_e32 v12, v127, v111
	v_fmac_f32_e32 v13, v127, v119
	v_fmac_f32_e32 v12, v128, v112
	v_fmac_f32_e32 v13, v128, v120
	v_fmac_f32_e32 v12, v129, v113
	v_fmac_f32_e32 v13, v129, v121
	v_fmac_f32_e32 v12, v130, v114
	v_fmac_f32_e32 v13, v130, v122
	v_fmac_f32_e32 v12, v131, v115
	v_fmac_f32_e32 v13, v131, v123
	global_load_dwordx4 v[108:111], v9, s[34:35] offset:192
	global_load_dwordx4 v[112:115], v9, s[34:35] offset:208
	global_load_dwordx4 v[116:119], v9, s[36:37] offset:192
	global_load_dwordx4 v[120:123], v9, s[36:37] offset:208
	global_load_dword v124, v4, s[100:101]
	s_add_u32 s100, s100, 0x2000
	s_addc_u32 s101, s101, 0
	global_load_dword v125, v4, s[100:101]
	s_add_u32 s100, s100, 0x2000
	s_addc_u32 s101, s101, 0
	global_load_dword v126, v4, s[100:101]
	s_add_u32 s100, s100, 0x2000
	s_addc_u32 s101, s101, 0
	global_load_dword v127, v4, s[100:101]
	s_add_u32 s100, s100, 0x2000
	s_addc_u32 s101, s101, 0
	global_load_dword v128, v4, s[100:101]
	s_add_u32 s100, s100, 0x2000
	s_addc_u32 s101, s101, 0
	global_load_dword v129, v4, s[100:101]
	s_add_u32 s100, s100, 0x2000
	s_addc_u32 s101, s101, 0
	global_load_dword v130, v4, s[100:101]
	s_add_u32 s100, s100, 0x2000
	s_addc_u32 s101, s101, 0
	global_load_dword v131, v4, s[100:101]
	s_add_u32 s100, s100, 0x2000
	s_addc_u32 s101, s101, 0
	s_waitcnt vmcnt(36)
	v_fmac_f32_e32 v12, v148, v132
	v_fmac_f32_e32 v13, v148, v140
	v_fmac_f32_e32 v12, v149, v133
	v_fmac_f32_e32 v13, v149, v141
	v_fmac_f32_e32 v12, v150, v134
	v_fmac_f32_e32 v13, v150, v142
	v_fmac_f32_e32 v12, v151, v135
	v_fmac_f32_e32 v13, v151, v143
	v_fmac_f32_e32 v12, v152, v136
	v_fmac_f32_e32 v13, v152, v144
	v_fmac_f32_e32 v12, v153, v137
	v_fmac_f32_e32 v13, v153, v145
	v_fmac_f32_e32 v12, v154, v138
	v_fmac_f32_e32 v13, v154, v146
	v_fmac_f32_e32 v12, v155, v139
	v_fmac_f32_e32 v13, v155, v147
	global_load_dwordx4 v[132:135], v9, s[34:35] offset:224
	global_load_dwordx4 v[136:139], v9, s[34:35] offset:240
	global_load_dwordx4 v[140:143], v9, s[36:37] offset:224
	global_load_dwordx4 v[144:147], v9, s[36:37] offset:240
	global_load_dword v148, v4, s[100:101]
	s_add_u32 s100, s100, 0x2000
	s_addc_u32 s101, s101, 0
	global_load_dword v149, v4, s[100:101]
	s_add_u32 s100, s100, 0x2000
	s_addc_u32 s101, s101, 0
	global_load_dword v150, v4, s[100:101]
	s_add_u32 s100, s100, 0x2000
	s_addc_u32 s101, s101, 0
	global_load_dword v151, v4, s[100:101]
	s_add_u32 s100, s100, 0x2000
	s_addc_u32 s101, s101, 0
	global_load_dword v152, v4, s[100:101]
	s_add_u32 s100, s100, 0x2000
	s_addc_u32 s101, s101, 0
	global_load_dword v153, v4, s[100:101]
	s_add_u32 s100, s100, 0x2000
	s_addc_u32 s101, s101, 0
	global_load_dword v154, v4, s[100:101]
	s_add_u32 s100, s100, 0x2000
	s_addc_u32 s101, s101, 0
	global_load_dword v155, v4, s[100:101]
	s_add_u32 s100, s100, 0x2000
	s_addc_u32 s101, s101, 0
	s_waitcnt vmcnt(36)
	v_fmac_f32_e32 v12, v76, v60
	v_fmac_f32_e32 v13, v76, v68
	v_fmac_f32_e32 v12, v77, v61
	v_fmac_f32_e32 v13, v77, v69
	v_fmac_f32_e32 v12, v78, v62
	v_fmac_f32_e32 v13, v78, v70
	v_fmac_f32_e32 v12, v79, v63
	v_fmac_f32_e32 v13, v79, v71
	v_fmac_f32_e32 v12, v80, v64
	v_fmac_f32_e32 v13, v80, v72
	v_fmac_f32_e32 v12, v81, v65
	v_fmac_f32_e32 v13, v81, v73
	v_fmac_f32_e32 v12, v82, v66
	v_fmac_f32_e32 v13, v82, v74
	v_fmac_f32_e32 v12, v83, v67
	v_fmac_f32_e32 v13, v83, v75
	global_load_dwordx4 v[60:63], v9, s[34:35] offset:256
	global_load_dwordx4 v[64:67], v9, s[34:35] offset:272
	global_load_dwordx4 v[68:71], v9, s[36:37] offset:256
	global_load_dwordx4 v[72:75], v9, s[36:37] offset:272
	global_load_dword v76, v4, s[100:101]
	s_add_u32 s100, s100, 0x2000
	s_addc_u32 s101, s101, 0
	global_load_dword v77, v4, s[100:101]
	s_add_u32 s100, s100, 0x2000
	s_addc_u32 s101, s101, 0
	global_load_dword v78, v4, s[100:101]
	s_add_u32 s100, s100, 0x2000
	s_addc_u32 s101, s101, 0
	global_load_dword v79, v4, s[100:101]
	s_add_u32 s100, s100, 0x2000
	s_addc_u32 s101, s101, 0
	global_load_dword v80, v4, s[100:101]
	s_add_u32 s100, s100, 0x2000
	s_addc_u32 s101, s101, 0
	global_load_dword v81, v4, s[100:101]
	s_add_u32 s100, s100, 0x2000
	s_addc_u32 s101, s101, 0
	global_load_dword v82, v4, s[100:101]
	s_add_u32 s100, s100, 0x2000
	s_addc_u32 s101, s101, 0
	global_load_dword v83, v4, s[100:101]
	s_add_u32 s100, s100, 0x2000
	s_addc_u32 s101, s101, 0
	s_waitcnt vmcnt(36)
	v_fmac_f32_e32 v12, v100, v84
	v_fmac_f32_e32 v13, v100, v92
	v_fmac_f32_e32 v12, v101, v85
	v_fmac_f32_e32 v13, v101, v93
	v_fmac_f32_e32 v12, v102, v86
	v_fmac_f32_e32 v13, v102, v94
	v_fmac_f32_e32 v12, v103, v87
	v_fmac_f32_e32 v13, v103, v95
	v_fmac_f32_e32 v12, v104, v88
	v_fmac_f32_e32 v13, v104, v96
	v_fmac_f32_e32 v12, v105, v89
	v_fmac_f32_e32 v13, v105, v97
	v_fmac_f32_e32 v12, v106, v90
	v_fmac_f32_e32 v13, v106, v98
	v_fmac_f32_e32 v12, v107, v91
	v_fmac_f32_e32 v13, v107, v99
	global_load_dwordx4 v[84:87], v9, s[34:35] offset:288
	global_load_dwordx4 v[88:91], v9, s[34:35] offset:304
	global_load_dwordx4 v[92:95], v9, s[36:37] offset:288
	global_load_dwordx4 v[96:99], v9, s[36:37] offset:304
	global_load_dword v100, v4, s[100:101]
	s_add_u32 s100, s100, 0x2000
	s_addc_u32 s101, s101, 0
	global_load_dword v101, v4, s[100:101]
	s_add_u32 s100, s100, 0x2000
	s_addc_u32 s101, s101, 0
	global_load_dword v102, v4, s[100:101]
	s_add_u32 s100, s100, 0x2000
	s_addc_u32 s101, s101, 0
	global_load_dword v103, v4, s[100:101]
	s_add_u32 s100, s100, 0x2000
	s_addc_u32 s101, s101, 0
	global_load_dword v104, v4, s[100:101]
	s_add_u32 s100, s100, 0x2000
	s_addc_u32 s101, s101, 0
	global_load_dword v105, v4, s[100:101]
	s_add_u32 s100, s100, 0x2000
	s_addc_u32 s101, s101, 0
	global_load_dword v106, v4, s[100:101]
	s_add_u32 s100, s100, 0x2000
	s_addc_u32 s101, s101, 0
	global_load_dword v107, v4, s[100:101]
	s_add_u32 s100, s100, 0x2000
	s_addc_u32 s101, s101, 0
	s_waitcnt vmcnt(36)
	v_fmac_f32_e32 v12, v124, v108
	v_fmac_f32_e32 v13, v124, v116
	v_fmac_f32_e32 v12, v125, v109
	v_fmac_f32_e32 v13, v125, v117
	v_fmac_f32_e32 v12, v126, v110
	v_fmac_f32_e32 v13, v126, v118
	v_fmac_f32_e32 v12, v127, v111
	v_fmac_f32_e32 v13, v127, v119
	v_fmac_f32_e32 v12, v128, v112
	v_fmac_f32_e32 v13, v128, v120
	v_fmac_f32_e32 v12, v129, v113
	v_fmac_f32_e32 v13, v129, v121
	v_fmac_f32_e32 v12, v130, v114
	v_fmac_f32_e32 v13, v130, v122
	v_fmac_f32_e32 v12, v131, v115
	v_fmac_f32_e32 v13, v131, v123
	global_load_dwordx4 v[108:111], v9, s[34:35] offset:320
	global_load_dwordx4 v[112:115], v9, s[34:35] offset:336
	global_load_dwordx4 v[116:119], v9, s[36:37] offset:320
	global_load_dwordx4 v[120:123], v9, s[36:37] offset:336
	global_load_dword v124, v4, s[100:101]
	s_add_u32 s100, s100, 0x2000
	s_addc_u32 s101, s101, 0
	global_load_dword v125, v4, s[100:101]
	s_add_u32 s100, s100, 0x2000
	s_addc_u32 s101, s101, 0
	global_load_dword v126, v4, s[100:101]
	s_add_u32 s100, s100, 0x2000
	s_addc_u32 s101, s101, 0
	global_load_dword v127, v4, s[100:101]
	s_add_u32 s100, s100, 0x2000
	s_addc_u32 s101, s101, 0
	global_load_dword v128, v4, s[100:101]
	s_add_u32 s100, s100, 0x2000
	s_addc_u32 s101, s101, 0
	global_load_dword v129, v4, s[100:101]
	s_add_u32 s100, s100, 0x2000
	s_addc_u32 s101, s101, 0
	global_load_dword v130, v4, s[100:101]
	s_add_u32 s100, s100, 0x2000
	s_addc_u32 s101, s101, 0
	global_load_dword v131, v4, s[100:101]
	s_add_u32 s100, s100, 0x2000
	s_addc_u32 s101, s101, 0
	s_waitcnt vmcnt(36)
	v_fmac_f32_e32 v12, v148, v132
	v_fmac_f32_e32 v13, v148, v140
	v_fmac_f32_e32 v12, v149, v133
	v_fmac_f32_e32 v13, v149, v141
	v_fmac_f32_e32 v12, v150, v134
	v_fmac_f32_e32 v13, v150, v142
	v_fmac_f32_e32 v12, v151, v135
	v_fmac_f32_e32 v13, v151, v143
	v_fmac_f32_e32 v12, v152, v136
	v_fmac_f32_e32 v13, v152, v144
	v_fmac_f32_e32 v12, v153, v137
	v_fmac_f32_e32 v13, v153, v145
	v_fmac_f32_e32 v12, v154, v138
	v_fmac_f32_e32 v13, v154, v146
	v_fmac_f32_e32 v12, v155, v139
	v_fmac_f32_e32 v13, v155, v147
	global_load_dwordx4 v[132:135], v9, s[34:35] offset:352
	global_load_dwordx4 v[136:139], v9, s[34:35] offset:368
	global_load_dwordx4 v[140:143], v9, s[36:37] offset:352
	global_load_dwordx4 v[144:147], v9, s[36:37] offset:368
	global_load_dword v148, v4, s[100:101]
	s_add_u32 s100, s100, 0x2000
	s_addc_u32 s101, s101, 0
	global_load_dword v149, v4, s[100:101]
	s_add_u32 s100, s100, 0x2000
	s_addc_u32 s101, s101, 0
	global_load_dword v150, v4, s[100:101]
	s_add_u32 s100, s100, 0x2000
	s_addc_u32 s101, s101, 0
	global_load_dword v151, v4, s[100:101]
	s_add_u32 s100, s100, 0x2000
	s_addc_u32 s101, s101, 0
	global_load_dword v152, v4, s[100:101]
	s_add_u32 s100, s100, 0x2000
	s_addc_u32 s101, s101, 0
	global_load_dword v153, v4, s[100:101]
	s_add_u32 s100, s100, 0x2000
	s_addc_u32 s101, s101, 0
	global_load_dword v154, v4, s[100:101]
	s_add_u32 s100, s100, 0x2000
	s_addc_u32 s101, s101, 0
	global_load_dword v155, v4, s[100:101]
	s_add_u32 s100, s100, 0x2000
	s_addc_u32 s101, s101, 0
	s_waitcnt vmcnt(36)
	v_fmac_f32_e32 v12, v76, v60
	v_fmac_f32_e32 v13, v76, v68
	v_fmac_f32_e32 v12, v77, v61
	v_fmac_f32_e32 v13, v77, v69
	v_fmac_f32_e32 v12, v78, v62
	v_fmac_f32_e32 v13, v78, v70
	v_fmac_f32_e32 v12, v79, v63
	v_fmac_f32_e32 v13, v79, v71
	v_fmac_f32_e32 v12, v80, v64
	v_fmac_f32_e32 v13, v80, v72
	v_fmac_f32_e32 v12, v81, v65
	v_fmac_f32_e32 v13, v81, v73
	v_fmac_f32_e32 v12, v82, v66
	v_fmac_f32_e32 v13, v82, v74
	v_fmac_f32_e32 v12, v83, v67
	v_fmac_f32_e32 v13, v83, v75
	global_load_dwordx4 v[60:63], v9, s[34:35] offset:384
	global_load_dwordx4 v[64:67], v9, s[34:35] offset:400
	global_load_dwordx4 v[68:71], v9, s[36:37] offset:384
	global_load_dwordx4 v[72:75], v9, s[36:37] offset:400
	global_load_dword v76, v4, s[100:101]
	s_add_u32 s100, s100, 0x2000
	s_addc_u32 s101, s101, 0
	global_load_dword v77, v4, s[100:101]
	s_add_u32 s100, s100, 0x2000
	s_addc_u32 s101, s101, 0
	global_load_dword v78, v4, s[100:101]
	s_add_u32 s100, s100, 0x2000
	s_addc_u32 s101, s101, 0
	global_load_dword v79, v4, s[100:101]
	s_add_u32 s100, s100, 0x2000
	s_addc_u32 s101, s101, 0
	global_load_dword v80, v4, s[100:101]
	s_add_u32 s100, s100, 0x2000
	s_addc_u32 s101, s101, 0
	global_load_dword v81, v4, s[100:101]
	s_add_u32 s100, s100, 0x2000
	s_addc_u32 s101, s101, 0
	global_load_dword v82, v4, s[100:101]
	s_add_u32 s100, s100, 0x2000
	s_addc_u32 s101, s101, 0
	global_load_dword v83, v4, s[100:101]
	s_add_u32 s100, s100, 0x2000
	s_addc_u32 s101, s101, 0
	s_waitcnt vmcnt(36)
	v_fmac_f32_e32 v12, v100, v84
	v_fmac_f32_e32 v13, v100, v92
	v_fmac_f32_e32 v12, v101, v85
	v_fmac_f32_e32 v13, v101, v93
	v_fmac_f32_e32 v12, v102, v86
	v_fmac_f32_e32 v13, v102, v94
	v_fmac_f32_e32 v12, v103, v87
	v_fmac_f32_e32 v13, v103, v95
	v_fmac_f32_e32 v12, v104, v88
	v_fmac_f32_e32 v13, v104, v96
	v_fmac_f32_e32 v12, v105, v89
	v_fmac_f32_e32 v13, v105, v97
	v_fmac_f32_e32 v12, v106, v90
	v_fmac_f32_e32 v13, v106, v98
	v_fmac_f32_e32 v12, v107, v91
	v_fmac_f32_e32 v13, v107, v99
	global_load_dwordx4 v[84:87], v9, s[34:35] offset:416
	global_load_dwordx4 v[88:91], v9, s[34:35] offset:432
	global_load_dwordx4 v[92:95], v9, s[36:37] offset:416
	global_load_dwordx4 v[96:99], v9, s[36:37] offset:432
	global_load_dword v100, v4, s[100:101]
	s_add_u32 s100, s100, 0x2000
	s_addc_u32 s101, s101, 0
	global_load_dword v101, v4, s[100:101]
	s_add_u32 s100, s100, 0x2000
	s_addc_u32 s101, s101, 0
	global_load_dword v102, v4, s[100:101]
	s_add_u32 s100, s100, 0x2000
	s_addc_u32 s101, s101, 0
	global_load_dword v103, v4, s[100:101]
	s_add_u32 s100, s100, 0x2000
	s_addc_u32 s101, s101, 0
	global_load_dword v104, v4, s[100:101]
	s_add_u32 s100, s100, 0x2000
	s_addc_u32 s101, s101, 0
	global_load_dword v105, v4, s[100:101]
	s_add_u32 s100, s100, 0x2000
	s_addc_u32 s101, s101, 0
	global_load_dword v106, v4, s[100:101]
	s_add_u32 s100, s100, 0x2000
	s_addc_u32 s101, s101, 0
	global_load_dword v107, v4, s[100:101]
	s_add_u32 s100, s100, 0x2000
	s_addc_u32 s101, s101, 0
	s_waitcnt vmcnt(36)
	v_fmac_f32_e32 v12, v124, v108
	v_fmac_f32_e32 v13, v124, v116
	v_fmac_f32_e32 v12, v125, v109
	v_fmac_f32_e32 v13, v125, v117
	v_fmac_f32_e32 v12, v126, v110
	v_fmac_f32_e32 v13, v126, v118
	v_fmac_f32_e32 v12, v127, v111
	v_fmac_f32_e32 v13, v127, v119
	v_fmac_f32_e32 v12, v128, v112
	v_fmac_f32_e32 v13, v128, v120
	v_fmac_f32_e32 v12, v129, v113
	v_fmac_f32_e32 v13, v129, v121
	v_fmac_f32_e32 v12, v130, v114
	v_fmac_f32_e32 v13, v130, v122
	v_fmac_f32_e32 v12, v131, v115
	v_fmac_f32_e32 v13, v131, v123
	global_load_dwordx4 v[108:111], v9, s[34:35] offset:448
	global_load_dwordx4 v[112:115], v9, s[34:35] offset:464
	global_load_dwordx4 v[116:119], v9, s[36:37] offset:448
	global_load_dwordx4 v[120:123], v9, s[36:37] offset:464
	global_load_dword v124, v4, s[100:101]
	s_add_u32 s100, s100, 0x2000
	s_addc_u32 s101, s101, 0
	global_load_dword v125, v4, s[100:101]
	s_add_u32 s100, s100, 0x2000
	s_addc_u32 s101, s101, 0
	global_load_dword v126, v4, s[100:101]
	s_add_u32 s100, s100, 0x2000
	s_addc_u32 s101, s101, 0
	global_load_dword v127, v4, s[100:101]
	s_add_u32 s100, s100, 0x2000
	s_addc_u32 s101, s101, 0
	global_load_dword v128, v4, s[100:101]
	s_add_u32 s100, s100, 0x2000
	s_addc_u32 s101, s101, 0
	global_load_dword v129, v4, s[100:101]
	s_add_u32 s100, s100, 0x2000
	s_addc_u32 s101, s101, 0
	global_load_dword v130, v4, s[100:101]
	s_add_u32 s100, s100, 0x2000
	s_addc_u32 s101, s101, 0
	global_load_dword v131, v4, s[100:101]
	s_add_u32 s100, s100, 0x2000
	s_addc_u32 s101, s101, 0
	s_waitcnt vmcnt(36)
	v_fmac_f32_e32 v12, v148, v132
	v_fmac_f32_e32 v13, v148, v140
	v_fmac_f32_e32 v12, v149, v133
	v_fmac_f32_e32 v13, v149, v141
	v_fmac_f32_e32 v12, v150, v134
	v_fmac_f32_e32 v13, v150, v142
	v_fmac_f32_e32 v12, v151, v135
	v_fmac_f32_e32 v13, v151, v143
	v_fmac_f32_e32 v12, v152, v136
	v_fmac_f32_e32 v13, v152, v144
	v_fmac_f32_e32 v12, v153, v137
	v_fmac_f32_e32 v13, v153, v145
	v_fmac_f32_e32 v12, v154, v138
	v_fmac_f32_e32 v13, v154, v146
	v_fmac_f32_e32 v12, v155, v139
	v_fmac_f32_e32 v13, v155, v147
	global_load_dwordx4 v[132:135], v9, s[34:35] offset:480
	global_load_dwordx4 v[136:139], v9, s[34:35] offset:496
	global_load_dwordx4 v[140:143], v9, s[36:37] offset:480
	global_load_dwordx4 v[144:147], v9, s[36:37] offset:496
	global_load_dword v148, v4, s[100:101]
	s_add_u32 s100, s100, 0x2000
	s_addc_u32 s101, s101, 0
	global_load_dword v149, v4, s[100:101]
	s_add_u32 s100, s100, 0x2000
	s_addc_u32 s101, s101, 0
	global_load_dword v150, v4, s[100:101]
	s_add_u32 s100, s100, 0x2000
	s_addc_u32 s101, s101, 0
	global_load_dword v151, v4, s[100:101]
	s_add_u32 s100, s100, 0x2000
	s_addc_u32 s101, s101, 0
	global_load_dword v152, v4, s[100:101]
	s_add_u32 s100, s100, 0x2000
	s_addc_u32 s101, s101, 0
	global_load_dword v153, v4, s[100:101]
	s_add_u32 s100, s100, 0x2000
	s_addc_u32 s101, s101, 0
	global_load_dword v154, v4, s[100:101]
	s_add_u32 s100, s100, 0x2000
	s_addc_u32 s101, s101, 0
	global_load_dword v155, v4, s[100:101]
	s_add_u32 s100, s100, 0x2000
	s_addc_u32 s101, s101, 0
	s_waitcnt vmcnt(36)
	v_fmac_f32_e32 v12, v76, v60
	v_fmac_f32_e32 v13, v76, v68
	v_fmac_f32_e32 v12, v77, v61
	v_fmac_f32_e32 v13, v77, v69
	v_fmac_f32_e32 v12, v78, v62
	v_fmac_f32_e32 v13, v78, v70
	v_fmac_f32_e32 v12, v79, v63
	v_fmac_f32_e32 v13, v79, v71
	v_fmac_f32_e32 v12, v80, v64
	v_fmac_f32_e32 v13, v80, v72
	v_fmac_f32_e32 v12, v81, v65
	v_fmac_f32_e32 v13, v81, v73
	v_fmac_f32_e32 v12, v82, v66
	v_fmac_f32_e32 v13, v82, v74
	v_fmac_f32_e32 v12, v83, v67
	v_fmac_f32_e32 v13, v83, v75
	s_waitcnt vmcnt(24)
	v_fmac_f32_e32 v12, v100, v84
	v_fmac_f32_e32 v13, v100, v92
	v_fmac_f32_e32 v12, v101, v85
	v_fmac_f32_e32 v13, v101, v93
	v_fmac_f32_e32 v12, v102, v86
	v_fmac_f32_e32 v13, v102, v94
	v_fmac_f32_e32 v12, v103, v87
	v_fmac_f32_e32 v13, v103, v95
	v_fmac_f32_e32 v12, v104, v88
	v_fmac_f32_e32 v13, v104, v96
	v_fmac_f32_e32 v12, v105, v89
	v_fmac_f32_e32 v13, v105, v97
	v_fmac_f32_e32 v12, v106, v90
	v_fmac_f32_e32 v13, v106, v98
	v_fmac_f32_e32 v12, v107, v91
	v_fmac_f32_e32 v13, v107, v99
	s_waitcnt vmcnt(12)
	v_fmac_f32_e32 v12, v124, v108
	v_fmac_f32_e32 v13, v124, v116
	v_fmac_f32_e32 v12, v125, v109
	v_fmac_f32_e32 v13, v125, v117
	v_fmac_f32_e32 v12, v126, v110
	v_fmac_f32_e32 v13, v126, v118
	v_fmac_f32_e32 v12, v127, v111
	v_fmac_f32_e32 v13, v127, v119
	v_fmac_f32_e32 v12, v128, v112
	v_fmac_f32_e32 v13, v128, v120
	v_fmac_f32_e32 v12, v129, v113
	v_fmac_f32_e32 v13, v129, v121
	v_fmac_f32_e32 v12, v130, v114
	v_fmac_f32_e32 v13, v130, v122
	v_fmac_f32_e32 v12, v131, v115
	v_fmac_f32_e32 v13, v131, v123
	s_waitcnt vmcnt(0)
	v_fmac_f32_e32 v12, v148, v132
	v_fmac_f32_e32 v13, v148, v140
	v_fmac_f32_e32 v12, v149, v133
	v_fmac_f32_e32 v13, v149, v141
	v_fmac_f32_e32 v12, v150, v134
	v_fmac_f32_e32 v13, v150, v142
	v_fmac_f32_e32 v12, v151, v135
	v_fmac_f32_e32 v13, v151, v143
	v_fmac_f32_e32 v12, v152, v136
	v_fmac_f32_e32 v13, v152, v144
	v_fmac_f32_e32 v12, v153, v137
	v_fmac_f32_e32 v13, v153, v145
	v_fmac_f32_e32 v12, v154, v138
	v_fmac_f32_e32 v13, v154, v146
	v_fmac_f32_e32 v12, v155, v139
	v_fmac_f32_e32 v13, v155, v147
	v_cvt_f64_f32_e32 v[14:15], v12
	s_lshl_b64 s[8:9], s[8:9], 3
	v_ldexp_f64 v[14:15], v[14:15], 40
	s_add_u32 s8, s11, s8
	v_rndne_f64_e32 v[14:15], v[14:15]
	s_addc_u32 s9, s12, s9
	s_lshl_b32 s20, s31, 5
	v_ldexp_f64 v[16:17], v[14:15], s30
	s_and_b32 s20, s20, 0x3e00
	v_floor_f64_e32 v[16:17], v[16:17]
	v_cvt_f64_f32_e32 v[12:13], v13
	s_add_u32 s8, s8, s20
	v_fmac_f64_e32 v[14:15], 0xc1f00000, v[16:17]
	v_ldexp_f64 v[12:13], v[12:13], 40
	s_addc_u32 s9, s9, 0
	v_cvt_u32_f64_e32 v14, v[14:15]
	v_cvt_i32_f64_e32 v15, v[16:17]
	v_rndne_f64_e32 v[12:13], v[12:13]
	global_atomic_add_x2 v8, v[14:15], s[8:9]
	v_ldexp_f64 v[14:15], v[12:13], s30
	v_lshl_add_u64 v[0:1], s[8:9], 0, v[8:9]
	v_floor_f64_e32 v[14:15], v[14:15]
	v_fmac_f64_e32 v[12:13], 0xc1f00000, v[14:15]
	v_add_co_u32_e32 v0, vcc, 0x4000, v0
	v_cvt_u32_f64_e32 v12, v[12:13]
	v_cvt_i32_f64_e32 v13, v[14:15]
	v_addc_co_u32_e32 v1, vcc, 0, v1, vcc
	global_atomic_add_x2 v[0:1], v[12:13], off
	s_add_i32 s31, s31, s0
	s_add_i32 s13, s13, s14
	s_add_i32 s15, s15, s22
	s_cmpk_gt_i32 s31, 0x7ff
	s_cbranch_scc0 .LBB0_59
